# MoBA task prologue: Q-fragment, block-mean and both gate-row load groups issued together with counted waits (was three serial memory round trips)
# baseline (speedup 1.0000x reference)
.Lmb_task:
	s_sub_u32 s15, 7, s6
	s_cmp_eq_u32 s14, 0
	s_cselect_b32 s15, s15, s6
	s_lshl_b32 s22, s15, 2
	s_add_u32 s22, s22, 4
	s_lshl_b32 s30, s15, 17
	s_add_u32 s24, s8, s30
	s_addc_u32 s25, s9, 0
	s_mov_b32 s30, 0
	s_lshl_b32 s33, s15, 2
	s_add_u32 s33, s33, s30
	s_sub_u32 s31, s30, 4
	s_cmp_lt_u32 s30, 4
	s_cselect_b32 s31, s33, s31
	s_lshl_b32 s33, s31, 15
	s_add_u32 s33, s33, 0x800000
	s_add_u32 s26, s8, s33
	s_addc_u32 s27, s9, 0
	global_load_dwordx4 v[168:171], v132, s[26:27]
	global_load_dwordx4 v[172:175], v133, s[26:27]
	s_add_u32 s26, s26, 0x800000
	s_addc_u32 s27, s27, 0
	global_load_dwordx4 v[176:179], v132, s[26:27]
	global_load_dwordx4 v[180:183], v133, s[26:27]
	v_and_b32_e32 v140, 15, v230
	s_lshl_b32 s30, s7, 5
	v_lshlrev_b32_e32 v140, 8, v140
	s_lshl_b32 s30, s7, 14
	v_add_u32_e32 v140, s30, v140
	v_lshrrev_b32_e32 v141, 4, v230
	v_lshl_add_u32 v157, v141, 4, v140
	s_add_u32 s28, s24, 0
	s_addc_u32 s29, s25, 0
	global_load_dwordx4 v[64:67], v157, s[28:29] offset:0
	global_load_dwordx4 v[68:71], v157, s[28:29] offset:64
	global_load_dwordx4 v[72:75], v157, s[28:29] offset:128
	global_load_dwordx4 v[76:79], v157, s[28:29] offset:192
	s_add_u32 s28, s24, 4096
	s_addc_u32 s29, s25, 0
	global_load_dwordx4 v[80:83], v157, s[28:29] offset:0
	global_load_dwordx4 v[84:87], v157, s[28:29] offset:64
	global_load_dwordx4 v[88:91], v157, s[28:29] offset:128
	global_load_dwordx4 v[92:95], v157, s[28:29] offset:192
	s_cmp_lt_u32 s15, 4
	s_cbranch_scc1 .Lmb_sel_small
	v_lshl_add_u32 v142, v141, 6, v140
	v_and_b32_e32 v143, 7, v230
	v_lshlrev_b32_e32 v143, 9, v143
	v_lshl_add_u32 v143, v141, 7, v143
	global_load_dwordx4 v[0:3], v143, s[12:13] offset:0
	global_load_dwordx4 v[4:7], v143, s[12:13] offset:16
	global_load_dwordx4 v[8:11], v143, s[12:13] offset:32
	global_load_dwordx4 v[12:15], v143, s[12:13] offset:48
	global_load_dwordx4 v[16:19], v143, s[12:13] offset:64
	global_load_dwordx4 v[20:23], v143, s[12:13] offset:80
	global_load_dwordx4 v[24:27], v143, s[12:13] offset:96
	global_load_dwordx4 v[28:31], v143, s[12:13] offset:112
	s_add_u32 s28, s24, 0
	s_addc_u32 s29, s25, 0
	global_load_dwordx4 v[96:99], v142, s[28:29] offset:0
	global_load_dwordx4 v[100:103], v142, s[28:29] offset:16
	global_load_dwordx4 v[104:107], v142, s[28:29] offset:32
	global_load_dwordx4 v[108:111], v142, s[28:29] offset:48
	s_add_u32 s28, s24, 4096
	s_addc_u32 s29, s25, 0
	global_load_dwordx4 v[204:207], v142, s[28:29] offset:0
	global_load_dwordx4 v[208:211], v142, s[28:29] offset:16
	global_load_dwordx4 v[212:215], v142, s[28:29] offset:32
	global_load_dwordx4 v[216:219], v142, s[28:29] offset:48
	s_waitcnt vmcnt(4)
	v_lshlrev_b32_e32 v32, 16, v96
	v_and_b32_e32 v33, 0xffff0000, v96
	v_lshlrev_b32_e32 v34, 16, v97
	v_and_b32_e32 v35, 0xffff0000, v97
	v_lshlrev_b32_e32 v36, 16, v98
	v_and_b32_e32 v37, 0xffff0000, v98
	v_lshlrev_b32_e32 v38, 16, v99
	v_and_b32_e32 v39, 0xffff0000, v99
	v_lshlrev_b32_e32 v40, 16, v100
	v_and_b32_e32 v41, 0xffff0000, v100
	v_lshlrev_b32_e32 v42, 16, v101
	v_and_b32_e32 v43, 0xffff0000, v101
	v_lshlrev_b32_e32 v44, 16, v102
	v_and_b32_e32 v45, 0xffff0000, v102
	v_lshlrev_b32_e32 v46, 16, v103
	v_and_b32_e32 v47, 0xffff0000, v103
	v_lshlrev_b32_e32 v48, 16, v104
	v_and_b32_e32 v49, 0xffff0000, v104
	v_lshlrev_b32_e32 v50, 16, v105
	v_and_b32_e32 v51, 0xffff0000, v105
	v_lshlrev_b32_e32 v52, 16, v106
	v_and_b32_e32 v53, 0xffff0000, v106
	v_lshlrev_b32_e32 v54, 16, v107
	v_and_b32_e32 v55, 0xffff0000, v107
	v_lshlrev_b32_e32 v56, 16, v108
	v_and_b32_e32 v57, 0xffff0000, v108
	v_lshlrev_b32_e32 v58, 16, v109
	v_and_b32_e32 v59, 0xffff0000, v109
	v_lshlrev_b32_e32 v60, 16, v110
	v_and_b32_e32 v61, 0xffff0000, v110
	v_lshlrev_b32_e32 v62, 16, v111
	v_and_b32_e32 v63, 0xffff0000, v111
	s_nop 1
	v_mfma_f32_16x16x4_f32 v[112:115], v0, v32, 0
	v_mfma_f32_16x16x4_f32 v[112:115], v1, v33, v[112:115]
	v_mfma_f32_16x16x4_f32 v[112:115], v2, v34, v[112:115]
	v_mfma_f32_16x16x4_f32 v[112:115], v3, v35, v[112:115]
	v_mfma_f32_16x16x4_f32 v[112:115], v4, v36, v[112:115]
	v_mfma_f32_16x16x4_f32 v[112:115], v5, v37, v[112:115]
	v_mfma_f32_16x16x4_f32 v[112:115], v6, v38, v[112:115]
	v_mfma_f32_16x16x4_f32 v[112:115], v7, v39, v[112:115]
	v_mfma_f32_16x16x4_f32 v[112:115], v8, v40, v[112:115]
	v_mfma_f32_16x16x4_f32 v[112:115], v9, v41, v[112:115]
	v_mfma_f32_16x16x4_f32 v[112:115], v10, v42, v[112:115]
	v_mfma_f32_16x16x4_f32 v[112:115], v11, v43, v[112:115]
	v_mfma_f32_16x16x4_f32 v[112:115], v12, v44, v[112:115]
	v_mfma_f32_16x16x4_f32 v[112:115], v13, v45, v[112:115]
	v_mfma_f32_16x16x4_f32 v[112:115], v14, v46, v[112:115]
	v_mfma_f32_16x16x4_f32 v[112:115], v15, v47, v[112:115]
	v_mfma_f32_16x16x4_f32 v[112:115], v16, v48, v[112:115]
	v_mfma_f32_16x16x4_f32 v[112:115], v17, v49, v[112:115]
	v_mfma_f32_16x16x4_f32 v[112:115], v18, v50, v[112:115]
	v_mfma_f32_16x16x4_f32 v[112:115], v19, v51, v[112:115]
	v_mfma_f32_16x16x4_f32 v[112:115], v20, v52, v[112:115]
	v_mfma_f32_16x16x4_f32 v[112:115], v21, v53, v[112:115]
	v_mfma_f32_16x16x4_f32 v[112:115], v22, v54, v[112:115]
	v_mfma_f32_16x16x4_f32 v[112:115], v23, v55, v[112:115]
	v_mfma_f32_16x16x4_f32 v[112:115], v24, v56, v[112:115]
	v_mfma_f32_16x16x4_f32 v[112:115], v25, v57, v[112:115]
	v_mfma_f32_16x16x4_f32 v[112:115], v26, v58, v[112:115]
	v_mfma_f32_16x16x4_f32 v[112:115], v27, v59, v[112:115]
	v_mfma_f32_16x16x4_f32 v[112:115], v28, v60, v[112:115]
	v_mfma_f32_16x16x4_f32 v[112:115], v29, v61, v[112:115]
	v_mfma_f32_16x16x4_f32 v[112:115], v30, v62, v[112:115]
	v_mfma_f32_16x16x4_f32 v[112:115], v31, v63, v[112:115]
	s_nop 10
	ds_bpermute_b32 v116, v228, v112
	ds_bpermute_b32 v117, v228, v113
	ds_bpermute_b32 v118, v228, v114
	ds_bpermute_b32 v119, v228, v115
	s_waitcnt lgkmcnt(0)
	s_cmp_gt_u32 s15, 0
	s_cselect_b64 s[56:57], -1, 0
	v_cndmask_b32_e64 v112, v134, v112, s[56:57]
	s_cmp_gt_u32 s15, 1
	s_cselect_b64 s[58:59], -1, 0
	v_cndmask_b32_e64 v113, v134, v113, s[58:59]
	s_cmp_gt_u32 s15, 2
	s_cselect_b64 s[64:65], -1, 0
	v_cndmask_b32_e64 v114, v134, v114, s[64:65]
	s_cmp_gt_u32 s15, 3
	s_cselect_b64 s[68:69], -1, 0
	v_cndmask_b32_e64 v115, v134, v115, s[68:69]
	s_cmp_gt_u32 s15, 4
	s_cselect_b64 s[56:57], -1, 0
	v_cndmask_b32_e64 v116, v134, v116, s[56:57]
	s_cmp_gt_u32 s15, 5
	s_cselect_b64 s[58:59], -1, 0
	v_cndmask_b32_e64 v117, v134, v117, s[58:59]
	s_cmp_gt_u32 s15, 6
	s_cselect_b64 s[64:65], -1, 0
	v_cndmask_b32_e64 v118, v134, v118, s[64:65]
	v_mov_b32_e32 v160, 0
	v_mov_b32_e32 v158, v134
	v_mov_b32_e32 v159, 0
	v_cmp_gt_f32_e32 vcc, v112, v158
	s_nop 1
	v_cndmask_b32_e32 v158, v158, v112, vcc
	v_cndmask_b32_e64 v159, v159, 0, vcc
	v_cmp_gt_f32_e32 vcc, v113, v158
	s_nop 1
	v_cndmask_b32_e32 v158, v158, v113, vcc
	v_cndmask_b32_e64 v159, v159, 1, vcc
	v_cmp_gt_f32_e32 vcc, v114, v158
	s_nop 1
	v_cndmask_b32_e32 v158, v158, v114, vcc
	v_cndmask_b32_e64 v159, v159, 2, vcc
	v_cmp_gt_f32_e32 vcc, v115, v158
	s_nop 1
	v_cndmask_b32_e32 v158, v158, v115, vcc
	v_cndmask_b32_e64 v159, v159, 3, vcc
	v_cmp_gt_f32_e32 vcc, v116, v158
	s_nop 1
	v_cndmask_b32_e32 v158, v158, v116, vcc
	v_cndmask_b32_e64 v159, v159, 4, vcc
	v_cmp_gt_f32_e32 vcc, v117, v158
	s_nop 1
	v_cndmask_b32_e32 v158, v158, v117, vcc
	v_cndmask_b32_e64 v159, v159, 5, vcc
	v_cmp_gt_f32_e32 vcc, v118, v158
	s_nop 1
	v_cndmask_b32_e32 v158, v158, v118, vcc
	v_cndmask_b32_e64 v159, v159, 6, vcc
	v_lshlrev_b32_e64 v161, v159, 1
	v_or_b32_e32 v160, v160, v161
	v_cmp_eq_u32_e64 s[56:57], 0, v159
	v_cmp_eq_u32_e64 s[58:59], 1, v159
	v_cmp_eq_u32_e64 s[64:65], 2, v159
	v_cmp_eq_u32_e64 s[68:69], 3, v159
	s_nop 1
	v_cndmask_b32_e64 v112, v112, v134, s[56:57]
	v_cndmask_b32_e64 v113, v113, v134, s[58:59]
	v_cndmask_b32_e64 v114, v114, v134, s[64:65]
	v_cndmask_b32_e64 v115, v115, v134, s[68:69]
	v_cmp_eq_u32_e64 s[56:57], 4, v159
	v_cmp_eq_u32_e64 s[58:59], 5, v159
	v_cmp_eq_u32_e64 s[64:65], 6, v159
	s_nop 1
	v_cndmask_b32_e64 v116, v116, v134, s[56:57]
	v_cndmask_b32_e64 v117, v117, v134, s[58:59]
	v_cndmask_b32_e64 v118, v118, v134, s[64:65]
	v_mov_b32_e32 v158, v134
	v_mov_b32_e32 v159, 0
	v_cmp_gt_f32_e32 vcc, v112, v158
	s_nop 1
	v_cndmask_b32_e32 v158, v158, v112, vcc
	v_cndmask_b32_e64 v159, v159, 0, vcc
	v_cmp_gt_f32_e32 vcc, v113, v158
	s_nop 1
	v_cndmask_b32_e32 v158, v158, v113, vcc
	v_cndmask_b32_e64 v159, v159, 1, vcc
	v_cmp_gt_f32_e32 vcc, v114, v158
	s_nop 1
	v_cndmask_b32_e32 v158, v158, v114, vcc
	v_cndmask_b32_e64 v159, v159, 2, vcc
	v_cmp_gt_f32_e32 vcc, v115, v158
	s_nop 1
	v_cndmask_b32_e32 v158, v158, v115, vcc
	v_cndmask_b32_e64 v159, v159, 3, vcc
	v_cmp_gt_f32_e32 vcc, v116, v158
	s_nop 1
	v_cndmask_b32_e32 v158, v158, v116, vcc
	v_cndmask_b32_e64 v159, v159, 4, vcc
	v_cmp_gt_f32_e32 vcc, v117, v158
	s_nop 1
	v_cndmask_b32_e32 v158, v158, v117, vcc
	v_cndmask_b32_e64 v159, v159, 5, vcc
	v_cmp_gt_f32_e32 vcc, v118, v158
	s_nop 1
	v_cndmask_b32_e32 v158, v158, v118, vcc
	v_cndmask_b32_e64 v159, v159, 6, vcc
	v_lshlrev_b32_e64 v161, v159, 1
	v_or_b32_e32 v160, v160, v161
	v_cmp_eq_u32_e64 s[56:57], 0, v159
	v_cmp_eq_u32_e64 s[58:59], 1, v159
	v_cmp_eq_u32_e64 s[64:65], 2, v159
	v_cmp_eq_u32_e64 s[68:69], 3, v159
	s_nop 1
	v_cndmask_b32_e64 v112, v112, v134, s[56:57]
	v_cndmask_b32_e64 v113, v113, v134, s[58:59]
	v_cndmask_b32_e64 v114, v114, v134, s[64:65]
	v_cndmask_b32_e64 v115, v115, v134, s[68:69]
	v_cmp_eq_u32_e64 s[56:57], 4, v159
	v_cmp_eq_u32_e64 s[58:59], 5, v159
	v_cmp_eq_u32_e64 s[64:65], 6, v159
	s_nop 1
	v_cndmask_b32_e64 v116, v116, v134, s[56:57]
	v_cndmask_b32_e64 v117, v117, v134, s[58:59]
	v_cndmask_b32_e64 v118, v118, v134, s[64:65]
	v_mov_b32_e32 v158, v134
	v_mov_b32_e32 v159, 0
	v_cmp_gt_f32_e32 vcc, v112, v158
	s_nop 1
	v_cndmask_b32_e32 v158, v158, v112, vcc
	v_cndmask_b32_e64 v159, v159, 0, vcc
	v_cmp_gt_f32_e32 vcc, v113, v158
	s_nop 1
	v_cndmask_b32_e32 v158, v158, v113, vcc
	v_cndmask_b32_e64 v159, v159, 1, vcc
	v_cmp_gt_f32_e32 vcc, v114, v158
	s_nop 1
	v_cndmask_b32_e32 v158, v158, v114, vcc
	v_cndmask_b32_e64 v159, v159, 2, vcc
	v_cmp_gt_f32_e32 vcc, v115, v158
	s_nop 1
	v_cndmask_b32_e32 v158, v158, v115, vcc
	v_cndmask_b32_e64 v159, v159, 3, vcc
	v_cmp_gt_f32_e32 vcc, v116, v158
	s_nop 1
	v_cndmask_b32_e32 v158, v158, v116, vcc
	v_cndmask_b32_e64 v159, v159, 4, vcc
	v_cmp_gt_f32_e32 vcc, v117, v158
	s_nop 1
	v_cndmask_b32_e32 v158, v158, v117, vcc
	v_cndmask_b32_e64 v159, v159, 5, vcc
	v_cmp_gt_f32_e32 vcc, v118, v158
	s_nop 1
	v_cndmask_b32_e32 v158, v158, v118, vcc
	v_cndmask_b32_e64 v159, v159, 6, vcc
	v_lshlrev_b32_e64 v161, v159, 1
	v_or_b32_e32 v160, v160, v161
	v_and_b32_e32 v161, 15, v230
	v_lshlrev_b32_e32 v161, 2, v161
	ds_bpermute_b32 v152, v161, v160
	s_waitcnt lgkmcnt(0)
	s_waitcnt vmcnt(0)
	v_lshlrev_b32_e32 v32, 16, v204
	v_and_b32_e32 v33, 0xffff0000, v204
	v_lshlrev_b32_e32 v34, 16, v205
	v_and_b32_e32 v35, 0xffff0000, v205
	v_lshlrev_b32_e32 v36, 16, v206
	v_and_b32_e32 v37, 0xffff0000, v206
	v_lshlrev_b32_e32 v38, 16, v207
	v_and_b32_e32 v39, 0xffff0000, v207
	v_lshlrev_b32_e32 v40, 16, v208
	v_and_b32_e32 v41, 0xffff0000, v208
	v_lshlrev_b32_e32 v42, 16, v209
	v_and_b32_e32 v43, 0xffff0000, v209
	v_lshlrev_b32_e32 v44, 16, v210
	v_and_b32_e32 v45, 0xffff0000, v210
	v_lshlrev_b32_e32 v46, 16, v211
	v_and_b32_e32 v47, 0xffff0000, v211
	v_lshlrev_b32_e32 v48, 16, v212
	v_and_b32_e32 v49, 0xffff0000, v212
	v_lshlrev_b32_e32 v50, 16, v213
	v_and_b32_e32 v51, 0xffff0000, v213
	v_lshlrev_b32_e32 v52, 16, v214
	v_and_b32_e32 v53, 0xffff0000, v214
	v_lshlrev_b32_e32 v54, 16, v215
	v_and_b32_e32 v55, 0xffff0000, v215
	v_lshlrev_b32_e32 v56, 16, v216
	v_and_b32_e32 v57, 0xffff0000, v216
	v_lshlrev_b32_e32 v58, 16, v217
	v_and_b32_e32 v59, 0xffff0000, v217
	v_lshlrev_b32_e32 v60, 16, v218
	v_and_b32_e32 v61, 0xffff0000, v218
	v_lshlrev_b32_e32 v62, 16, v219
	v_and_b32_e32 v63, 0xffff0000, v219
	s_nop 1
	v_mfma_f32_16x16x4_f32 v[112:115], v0, v32, 0
	v_mfma_f32_16x16x4_f32 v[112:115], v1, v33, v[112:115]
	v_mfma_f32_16x16x4_f32 v[112:115], v2, v34, v[112:115]
	v_mfma_f32_16x16x4_f32 v[112:115], v3, v35, v[112:115]
	v_mfma_f32_16x16x4_f32 v[112:115], v4, v36, v[112:115]
	v_mfma_f32_16x16x4_f32 v[112:115], v5, v37, v[112:115]
	v_mfma_f32_16x16x4_f32 v[112:115], v6, v38, v[112:115]
	v_mfma_f32_16x16x4_f32 v[112:115], v7, v39, v[112:115]
	v_mfma_f32_16x16x4_f32 v[112:115], v8, v40, v[112:115]
	v_mfma_f32_16x16x4_f32 v[112:115], v9, v41, v[112:115]
	v_mfma_f32_16x16x4_f32 v[112:115], v10, v42, v[112:115]
	v_mfma_f32_16x16x4_f32 v[112:115], v11, v43, v[112:115]
	v_mfma_f32_16x16x4_f32 v[112:115], v12, v44, v[112:115]
	v_mfma_f32_16x16x4_f32 v[112:115], v13, v45, v[112:115]
	v_mfma_f32_16x16x4_f32 v[112:115], v14, v46, v[112:115]
	v_mfma_f32_16x16x4_f32 v[112:115], v15, v47, v[112:115]
	v_mfma_f32_16x16x4_f32 v[112:115], v16, v48, v[112:115]
	v_mfma_f32_16x16x4_f32 v[112:115], v17, v49, v[112:115]
	v_mfma_f32_16x16x4_f32 v[112:115], v18, v50, v[112:115]
	v_mfma_f32_16x16x4_f32 v[112:115], v19, v51, v[112:115]
	v_mfma_f32_16x16x4_f32 v[112:115], v20, v52, v[112:115]
	v_mfma_f32_16x16x4_f32 v[112:115], v21, v53, v[112:115]
	v_mfma_f32_16x16x4_f32 v[112:115], v22, v54, v[112:115]
	v_mfma_f32_16x16x4_f32 v[112:115], v23, v55, v[112:115]
	v_mfma_f32_16x16x4_f32 v[112:115], v24, v56, v[112:115]
	v_mfma_f32_16x16x4_f32 v[112:115], v25, v57, v[112:115]
	v_mfma_f32_16x16x4_f32 v[112:115], v26, v58, v[112:115]
	v_mfma_f32_16x16x4_f32 v[112:115], v27, v59, v[112:115]
	v_mfma_f32_16x16x4_f32 v[112:115], v28, v60, v[112:115]
	v_mfma_f32_16x16x4_f32 v[112:115], v29, v61, v[112:115]
	v_mfma_f32_16x16x4_f32 v[112:115], v30, v62, v[112:115]
	v_mfma_f32_16x16x4_f32 v[112:115], v31, v63, v[112:115]
	s_nop 10
	ds_bpermute_b32 v116, v228, v112
	ds_bpermute_b32 v117, v228, v113
	ds_bpermute_b32 v118, v228, v114
	ds_bpermute_b32 v119, v228, v115
	s_waitcnt lgkmcnt(0)
	s_cmp_gt_u32 s15, 0
	s_cselect_b64 s[56:57], -1, 0
	v_cndmask_b32_e64 v112, v134, v112, s[56:57]
	s_cmp_gt_u32 s15, 1
	s_cselect_b64 s[58:59], -1, 0
	v_cndmask_b32_e64 v113, v134, v113, s[58:59]
	s_cmp_gt_u32 s15, 2
	s_cselect_b64 s[64:65], -1, 0
	v_cndmask_b32_e64 v114, v134, v114, s[64:65]
	s_cmp_gt_u32 s15, 3
	s_cselect_b64 s[68:69], -1, 0
	v_cndmask_b32_e64 v115, v134, v115, s[68:69]
	s_cmp_gt_u32 s15, 4
	s_cselect_b64 s[56:57], -1, 0
	v_cndmask_b32_e64 v116, v134, v116, s[56:57]
	s_cmp_gt_u32 s15, 5
	s_cselect_b64 s[58:59], -1, 0
	v_cndmask_b32_e64 v117, v134, v117, s[58:59]
	s_cmp_gt_u32 s15, 6
	s_cselect_b64 s[64:65], -1, 0
	v_cndmask_b32_e64 v118, v134, v118, s[64:65]
	v_mov_b32_e32 v160, 0
	v_mov_b32_e32 v158, v134
	v_mov_b32_e32 v159, 0
	v_cmp_gt_f32_e32 vcc, v112, v158
	s_nop 1
	v_cndmask_b32_e32 v158, v158, v112, vcc
	v_cndmask_b32_e64 v159, v159, 0, vcc
	v_cmp_gt_f32_e32 vcc, v113, v158
	s_nop 1
	v_cndmask_b32_e32 v158, v158, v113, vcc
	v_cndmask_b32_e64 v159, v159, 1, vcc
	v_cmp_gt_f32_e32 vcc, v114, v158
	s_nop 1
	v_cndmask_b32_e32 v158, v158, v114, vcc
	v_cndmask_b32_e64 v159, v159, 2, vcc
	v_cmp_gt_f32_e32 vcc, v115, v158
	s_nop 1
	v_cndmask_b32_e32 v158, v158, v115, vcc
	v_cndmask_b32_e64 v159, v159, 3, vcc
	v_cmp_gt_f32_e32 vcc, v116, v158
	s_nop 1
	v_cndmask_b32_e32 v158, v158, v116, vcc
	v_cndmask_b32_e64 v159, v159, 4, vcc
	v_cmp_gt_f32_e32 vcc, v117, v158
	s_nop 1
	v_cndmask_b32_e32 v158, v158, v117, vcc
	v_cndmask_b32_e64 v159, v159, 5, vcc
	v_cmp_gt_f32_e32 vcc, v118, v158
	s_nop 1
	v_cndmask_b32_e32 v158, v158, v118, vcc
	v_cndmask_b32_e64 v159, v159, 6, vcc
	v_lshlrev_b32_e64 v161, v159, 1
	v_or_b32_e32 v160, v160, v161
	v_cmp_eq_u32_e64 s[56:57], 0, v159
	v_cmp_eq_u32_e64 s[58:59], 1, v159
	v_cmp_eq_u32_e64 s[64:65], 2, v159
	v_cmp_eq_u32_e64 s[68:69], 3, v159
	s_nop 1
	v_cndmask_b32_e64 v112, v112, v134, s[56:57]
	v_cndmask_b32_e64 v113, v113, v134, s[58:59]
	v_cndmask_b32_e64 v114, v114, v134, s[64:65]
	v_cndmask_b32_e64 v115, v115, v134, s[68:69]
	v_cmp_eq_u32_e64 s[56:57], 4, v159
	v_cmp_eq_u32_e64 s[58:59], 5, v159
	v_cmp_eq_u32_e64 s[64:65], 6, v159
	s_nop 1
	v_cndmask_b32_e64 v116, v116, v134, s[56:57]
	v_cndmask_b32_e64 v117, v117, v134, s[58:59]
	v_cndmask_b32_e64 v118, v118, v134, s[64:65]
	v_mov_b32_e32 v158, v134
	v_mov_b32_e32 v159, 0
	v_cmp_gt_f32_e32 vcc, v112, v158
	s_nop 1
	v_cndmask_b32_e32 v158, v158, v112, vcc
	v_cndmask_b32_e64 v159, v159, 0, vcc
	v_cmp_gt_f32_e32 vcc, v113, v158
	s_nop 1
	v_cndmask_b32_e32 v158, v158, v113, vcc
	v_cndmask_b32_e64 v159, v159, 1, vcc
	v_cmp_gt_f32_e32 vcc, v114, v158
	s_nop 1
	v_cndmask_b32_e32 v158, v158, v114, vcc
	v_cndmask_b32_e64 v159, v159, 2, vcc
	v_cmp_gt_f32_e32 vcc, v115, v158
	s_nop 1
	v_cndmask_b32_e32 v158, v158, v115, vcc
	v_cndmask_b32_e64 v159, v159, 3, vcc
	v_cmp_gt_f32_e32 vcc, v116, v158
	s_nop 1
	v_cndmask_b32_e32 v158, v158, v116, vcc
	v_cndmask_b32_e64 v159, v159, 4, vcc
	v_cmp_gt_f32_e32 vcc, v117, v158
	s_nop 1
	v_cndmask_b32_e32 v158, v158, v117, vcc
	v_cndmask_b32_e64 v159, v159, 5, vcc
	v_cmp_gt_f32_e32 vcc, v118, v158
	s_nop 1
	v_cndmask_b32_e32 v158, v158, v118, vcc
	v_cndmask_b32_e64 v159, v159, 6, vcc
	v_lshlrev_b32_e64 v161, v159, 1
	v_or_b32_e32 v160, v160, v161
	v_cmp_eq_u32_e64 s[56:57], 0, v159
	v_cmp_eq_u32_e64 s[58:59], 1, v159
	v_cmp_eq_u32_e64 s[64:65], 2, v159
	v_cmp_eq_u32_e64 s[68:69], 3, v159
	s_nop 1
	v_cndmask_b32_e64 v112, v112, v134, s[56:57]
	v_cndmask_b32_e64 v113, v113, v134, s[58:59]
	v_cndmask_b32_e64 v114, v114, v134, s[64:65]
	v_cndmask_b32_e64 v115, v115, v134, s[68:69]
	v_cmp_eq_u32_e64 s[56:57], 4, v159
	v_cmp_eq_u32_e64 s[58:59], 5, v159
	v_cmp_eq_u32_e64 s[64:65], 6, v159
	s_nop 1
	v_cndmask_b32_e64 v116, v116, v134, s[56:57]
	v_cndmask_b32_e64 v117, v117, v134, s[58:59]
	v_cndmask_b32_e64 v118, v118, v134, s[64:65]
	v_mov_b32_e32 v158, v134
	v_mov_b32_e32 v159, 0
	v_cmp_gt_f32_e32 vcc, v112, v158
	s_nop 1
	v_cndmask_b32_e32 v158, v158, v112, vcc
	v_cndmask_b32_e64 v159, v159, 0, vcc
	v_cmp_gt_f32_e32 vcc, v113, v158
	s_nop 1
	v_cndmask_b32_e32 v158, v158, v113, vcc
	v_cndmask_b32_e64 v159, v159, 1, vcc
	v_cmp_gt_f32_e32 vcc, v114, v158
	s_nop 1
	v_cndmask_b32_e32 v158, v158, v114, vcc
	v_cndmask_b32_e64 v159, v159, 2, vcc
	v_cmp_gt_f32_e32 vcc, v115, v158
	s_nop 1
	v_cndmask_b32_e32 v158, v158, v115, vcc
	v_cndmask_b32_e64 v159, v159, 3, vcc
	v_cmp_gt_f32_e32 vcc, v116, v158
	s_nop 1
	v_cndmask_b32_e32 v158, v158, v116, vcc
	v_cndmask_b32_e64 v159, v159, 4, vcc
	v_cmp_gt_f32_e32 vcc, v117, v158
	s_nop 1
	v_cndmask_b32_e32 v158, v158, v117, vcc
	v_cndmask_b32_e64 v159, v159, 5, vcc
	v_cmp_gt_f32_e32 vcc, v118, v158
	s_nop 1
	v_cndmask_b32_e32 v158, v158, v118, vcc
	v_cndmask_b32_e64 v159, v159, 6, vcc
	v_lshlrev_b32_e64 v161, v159, 1
	v_or_b32_e32 v160, v160, v161
	v_and_b32_e32 v161, 15, v230
	v_lshlrev_b32_e32 v161, 2, v161
	ds_bpermute_b32 v153, v161, v160
	s_waitcnt lgkmcnt(0)
	s_branch .Lmb_sel_done

.Lmb_sel_done:
	s_waitcnt vmcnt(0)
	v_lshlrev_b32_e32 v143, 16, v64
	v_and_b32_e32 v157, 0xffff0000, v64
	v_mul_f32_e32 v143, s38, v143
	v_mul_f32_e32 v157, s38, v157
	v_cvt_pk_bf16_f32 v64, v143, v157
	v_lshlrev_b32_e32 v143, 16, v65
	v_and_b32_e32 v157, 0xffff0000, v65
	v_mul_f32_e32 v143, s38, v143
	v_mul_f32_e32 v157, s38, v157
	v_cvt_pk_bf16_f32 v65, v143, v157
	v_lshlrev_b32_e32 v143, 16, v66
	v_and_b32_e32 v157, 0xffff0000, v66
	v_mul_f32_e32 v143, s38, v143
	v_mul_f32_e32 v157, s38, v157
	v_cvt_pk_bf16_f32 v66, v143, v157
	v_lshlrev_b32_e32 v143, 16, v67
	v_and_b32_e32 v157, 0xffff0000, v67
	v_mul_f32_e32 v143, s38, v143
	v_mul_f32_e32 v157, s38, v157
	v_cvt_pk_bf16_f32 v67, v143, v157
	v_lshlrev_b32_e32 v143, 16, v68
	v_and_b32_e32 v157, 0xffff0000, v68
	v_mul_f32_e32 v143, s38, v143
	v_mul_f32_e32 v157, s38, v157
	v_cvt_pk_bf16_f32 v68, v143, v157
	v_lshlrev_b32_e32 v143, 16, v69
	v_and_b32_e32 v157, 0xffff0000, v69
	v_mul_f32_e32 v143, s38, v143
	v_mul_f32_e32 v157, s38, v157
	v_cvt_pk_bf16_f32 v69, v143, v157
	v_lshlrev_b32_e32 v143, 16, v70
	v_and_b32_e32 v157, 0xffff0000, v70
	v_mul_f32_e32 v143, s38, v143
	v_mul_f32_e32 v157, s38, v157
	v_cvt_pk_bf16_f32 v70, v143, v157
	v_lshlrev_b32_e32 v143, 16, v71
	v_and_b32_e32 v157, 0xffff0000, v71
	v_mul_f32_e32 v143, s38, v143
	v_mul_f32_e32 v157, s38, v157
	v_cvt_pk_bf16_f32 v71, v143, v157
	v_lshlrev_b32_e32 v143, 16, v72
	v_and_b32_e32 v157, 0xffff0000, v72
	v_mul_f32_e32 v143, s38, v143
	v_mul_f32_e32 v157, s38, v157
	v_cvt_pk_bf16_f32 v72, v143, v157
	v_lshlrev_b32_e32 v143, 16, v73
	v_and_b32_e32 v157, 0xffff0000, v73
	v_mul_f32_e32 v143, s38, v143
	v_mul_f32_e32 v157, s38, v157
	v_cvt_pk_bf16_f32 v73, v143, v157
	v_lshlrev_b32_e32 v143, 16, v74
	v_and_b32_e32 v157, 0xffff0000, v74
	v_mul_f32_e32 v143, s38, v143
	v_mul_f32_e32 v157, s38, v157
	v_cvt_pk_bf16_f32 v74, v143, v157
	v_lshlrev_b32_e32 v143, 16, v75
	v_and_b32_e32 v157, 0xffff0000, v75
	v_mul_f32_e32 v143, s38, v143
	v_mul_f32_e32 v157, s38, v157
	v_cvt_pk_bf16_f32 v75, v143, v157
	v_lshlrev_b32_e32 v143, 16, v76
	v_and_b32_e32 v157, 0xffff0000, v76
	v_mul_f32_e32 v143, s38, v143
	v_mul_f32_e32 v157, s38, v157
	v_cvt_pk_bf16_f32 v76, v143, v157
	v_lshlrev_b32_e32 v143, 16, v77
	v_and_b32_e32 v157, 0xffff0000, v77
	v_mul_f32_e32 v143, s38, v143
	v_mul_f32_e32 v157, s38, v157
	v_cvt_pk_bf16_f32 v77, v143, v157
	v_lshlrev_b32_e32 v143, 16, v78
	v_and_b32_e32 v157, 0xffff0000, v78
	v_mul_f32_e32 v143, s38, v143
	v_mul_f32_e32 v157, s38, v157
	v_cvt_pk_bf16_f32 v78, v143, v157
	v_lshlrev_b32_e32 v143, 16, v79
	v_and_b32_e32 v157, 0xffff0000, v79
	v_mul_f32_e32 v143, s38, v143
	v_mul_f32_e32 v157, s38, v157
	v_cvt_pk_bf16_f32 v79, v143, v157
	v_lshlrev_b32_e32 v143, 16, v80
	v_and_b32_e32 v157, 0xffff0000, v80
	v_mul_f32_e32 v143, s38, v143
	v_mul_f32_e32 v157, s38, v157
	v_cvt_pk_bf16_f32 v80, v143, v157
	v_lshlrev_b32_e32 v143, 16, v81
	v_and_b32_e32 v157, 0xffff0000, v81
	v_mul_f32_e32 v143, s38, v143
	v_mul_f32_e32 v157, s38, v157
	v_cvt_pk_bf16_f32 v81, v143, v157
	v_lshlrev_b32_e32 v143, 16, v82
	v_and_b32_e32 v157, 0xffff0000, v82
	v_mul_f32_e32 v143, s38, v143
	v_mul_f32_e32 v157, s38, v157
	v_cvt_pk_bf16_f32 v82, v143, v157
	v_lshlrev_b32_e32 v143, 16, v83
	v_and_b32_e32 v157, 0xffff0000, v83
	v_mul_f32_e32 v143, s38, v143
	v_mul_f32_e32 v157, s38, v157
	v_cvt_pk_bf16_f32 v83, v143, v157
	v_lshlrev_b32_e32 v143, 16, v84
	v_and_b32_e32 v157, 0xffff0000, v84
	v_mul_f32_e32 v143, s38, v143
	v_mul_f32_e32 v157, s38, v157
	v_cvt_pk_bf16_f32 v84, v143, v157
	v_lshlrev_b32_e32 v143, 16, v85
	v_and_b32_e32 v157, 0xffff0000, v85
	v_mul_f32_e32 v143, s38, v143
	v_mul_f32_e32 v157, s38, v157
	v_cvt_pk_bf16_f32 v85, v143, v157
	v_lshlrev_b32_e32 v143, 16, v86
	v_and_b32_e32 v157, 0xffff0000, v86
	v_mul_f32_e32 v143, s38, v143
	v_mul_f32_e32 v157, s38, v157
	v_cvt_pk_bf16_f32 v86, v143, v157
	v_lshlrev_b32_e32 v143, 16, v87
	v_and_b32_e32 v157, 0xffff0000, v87
	v_mul_f32_e32 v143, s38, v143
	v_mul_f32_e32 v157, s38, v157
	v_cvt_pk_bf16_f32 v87, v143, v157
	v_lshlrev_b32_e32 v143, 16, v88
	v_and_b32_e32 v157, 0xffff0000, v88
	v_mul_f32_e32 v143, s38, v143
	v_mul_f32_e32 v157, s38, v157
	v_cvt_pk_bf16_f32 v88, v143, v157
	v_lshlrev_b32_e32 v143, 16, v89
	v_and_b32_e32 v157, 0xffff0000, v89
	v_mul_f32_e32 v143, s38, v143
	v_mul_f32_e32 v157, s38, v157
	v_cvt_pk_bf16_f32 v89, v143, v157
	v_lshlrev_b32_e32 v143, 16, v90
	v_and_b32_e32 v157, 0xffff0000, v90
	v_mul_f32_e32 v143, s38, v143
	v_mul_f32_e32 v157, s38, v157
	v_cvt_pk_bf16_f32 v90, v143, v157
	v_lshlrev_b32_e32 v143, 16, v91
	v_and_b32_e32 v157, 0xffff0000, v91
	v_mul_f32_e32 v143, s38, v143
	v_mul_f32_e32 v157, s38, v157
	v_cvt_pk_bf16_f32 v91, v143, v157
	v_lshlrev_b32_e32 v143, 16, v92
	v_and_b32_e32 v157, 0xffff0000, v92
	v_mul_f32_e32 v143, s38, v143
	v_mul_f32_e32 v157, s38, v157
	v_cvt_pk_bf16_f32 v92, v143, v157
	v_lshlrev_b32_e32 v143, 16, v93
	v_and_b32_e32 v157, 0xffff0000, v93
	v_mul_f32_e32 v143, s38, v143
	v_mul_f32_e32 v157, s38, v157
	v_cvt_pk_bf16_f32 v93, v143, v157
	v_lshlrev_b32_e32 v143, 16, v94
	v_and_b32_e32 v157, 0xffff0000, v94
	v_mul_f32_e32 v143, s38, v143
	v_mul_f32_e32 v157, s38, v157
	v_cvt_pk_bf16_f32 v94, v143, v157
	v_lshlrev_b32_e32 v143, 16, v95
	v_and_b32_e32 v157, 0xffff0000, v95
	v_mul_f32_e32 v143, s38, v143
	v_mul_f32_e32 v157, s38, v157
	v_cvt_pk_bf16_f32 v95, v143, v157
	v_mov_b32_e32 v0, 0
	v_mov_b32_e32 v1, 0
	v_mov_b32_e32 v2, 0
	v_mov_b32_e32 v3, 0
	v_mov_b32_e32 v4, 0
	v_mov_b32_e32 v5, 0
	v_mov_b32_e32 v6, 0
	v_mov_b32_e32 v7, 0
	v_mov_b32_e32 v8, 0
	v_mov_b32_e32 v9, 0
	v_mov_b32_e32 v10, 0
	v_mov_b32_e32 v11, 0
	v_mov_b32_e32 v12, 0
	v_mov_b32_e32 v13, 0
	v_mov_b32_e32 v14, 0
	v_mov_b32_e32 v15, 0
	v_mov_b32_e32 v16, 0
	v_mov_b32_e32 v17, 0
	v_mov_b32_e32 v18, 0
	v_mov_b32_e32 v19, 0
	v_mov_b32_e32 v20, 0
	v_mov_b32_e32 v21, 0
	v_mov_b32_e32 v22, 0
	v_mov_b32_e32 v23, 0
	v_mov_b32_e32 v24, 0
	v_mov_b32_e32 v25, 0
	v_mov_b32_e32 v26, 0
	v_mov_b32_e32 v27, 0
	v_mov_b32_e32 v28, 0
	v_mov_b32_e32 v29, 0
	v_mov_b32_e32 v30, 0
	v_mov_b32_e32 v31, 0
	v_mov_b32_e32 v32, 0
	v_mov_b32_e32 v33, 0
	v_mov_b32_e32 v34, 0
	v_mov_b32_e32 v35, 0
	v_mov_b32_e32 v36, 0
	v_mov_b32_e32 v37, 0
	v_mov_b32_e32 v38, 0
	v_mov_b32_e32 v39, 0
	v_mov_b32_e32 v40, 0
	v_mov_b32_e32 v41, 0
	v_mov_b32_e32 v42, 0
	v_mov_b32_e32 v43, 0
	v_mov_b32_e32 v44, 0
	v_mov_b32_e32 v45, 0
	v_mov_b32_e32 v46, 0
	v_mov_b32_e32 v47, 0
	v_mov_b32_e32 v48, 0
	v_mov_b32_e32 v49, 0
	v_mov_b32_e32 v50, 0
	v_mov_b32_e32 v51, 0
	v_mov_b32_e32 v52, 0
	v_mov_b32_e32 v53, 0
	v_mov_b32_e32 v54, 0
	v_mov_b32_e32 v55, 0
	v_mov_b32_e32 v56, 0
	v_mov_b32_e32 v57, 0
	v_mov_b32_e32 v58, 0
	v_mov_b32_e32 v59, 0
	v_mov_b32_e32 v60, 0
	v_mov_b32_e32 v61, 0
	v_mov_b32_e32 v62, 0
	v_mov_b32_e32 v63, 0
	v_mov_b32_e32 v148, 0xf149f2ca
	v_mov_b32_e32 v150, 0
	v_mov_b32_e32 v149, 0xf149f2ca
	v_mov_b32_e32 v151, 0
	v_xor_b32_e32 v130, 65536, v130
	v_xor_b32_e32 v131, 65536, v131
	s_waitcnt vmcnt(0)
	ds_write_b128 v130, v[168:171]
	ds_write_b128 v130, v[172:175] offset:8704
	ds_write_b128 v131, v[176:179]
	ds_write_b128 v131, v[180:183] offset:9216
	v_xor_b32_e32 v130, 65536, v130
	v_xor_b32_e32 v131, 65536, v131
	s_mov_b32 s30, 1
	s_lshl_b32 s33, s15, 2
	s_add_u32 s33, s33, s30
	s_sub_u32 s31, s30, 4
	s_cmp_lt_u32 s30, 4
	s_cselect_b32 s31, s33, s31
	s_lshl_b32 s33, s31, 15
	s_add_u32 s33, s33, 0x800000
	s_add_u32 s26, s8, s33
	s_addc_u32 s27, s9, 0
	global_load_dwordx4 v[168:171], v132, s[26:27]
	global_load_dwordx4 v[172:175], v133, s[26:27]
	s_add_u32 s26, s26, 0x800000
	s_addc_u32 s27, s27, 0
	global_load_dwordx4 v[176:179], v132, s[26:27]
	global_load_dwordx4 v[180:183], v133, s[26:27]
	s_mov_b32 s23, 0
	s_waitcnt lgkmcnt(0)
	s_barrier
